# speedup vs baseline: 1.0044x; 1.0015x over previous
; DEV void sb_item(const Params& p, int item, unsigned char* smem) {
;   const int qb = 63 - (item & 63), h = (item >> 6) & 3, b = item >> 8;
;   const int tid = tidx(), w = tid >> 6, lane = tid & 63, fr = lane & 15, fq = lane >> 4;
;   u16* sP = (u16*)(smem + L_PW) + w * RW * VS;
;   int* flags = (int*)(smem + L_FLAG);
;   const u16* base = p.proj + (size_t)b * SEQ * DIN;
;   const int q0 = qb * QR + w * RW;
;   bf16x8 qf[MT][4];
;   load_qfrags(base + (size_t)q0 * DIN + C_SQ + h * 128, qf, fr, fq);
;   f32x4 o[MT][8];
;   float run[MT][4];
; #pragma unroll
;   for (int mt = 0; mt < MT; ++mt) {
; #pragma unroll
;     for (int nt = 0; nt < 8; ++nt) o[mt][nt] = (f32x4){0.f, 0.f, 0.f, 0.f};
; #pragma unroll
;     for (int j = 0; j < 4; ++j) run[mt][j] = 0.f;
;   }
;   const float scale = 0.08838834764831845f;
;   uint4 kq0, kq1, vq0, vq1;
;   {
;     const int kt0 = (qb * QR + QR - 1) / 64;
;     kv_load(base + (size_t)(kt0 * 64) * DIN + C_SK + h * 128, base + (size_t)(kt0 * 64) * DIN + C_SV + h * 128, kq0, kq1, vq0, vq1, tid);
;   }
;   __syncthreads();
;   int it = 0;
;     ...
;     u16* sK = (u16*)(smem + L_K + (it & 1) * KB_B); u16* sVt = (u16*)(smem + L_VT + (it & 1) * VB_B);
;     kv_store(kq0, kq1, vq0, vq1, sK, sVt, tid);
;     if (kt > 0) kv_load(base + (size_t)((kt - 1) * 64) * DIN + C_SK + h * 128, base + (size_t)((kt - 1) * 64) * DIN + C_SV + h * 128, kq0, kq1, vq0, vq1, tid);
;     __syncthreads();
.LBB0_422:
	s_ashr_i32 s92, s34, 8
	v_readfirstlane_b32 s0, v160
	s_andn2_b32 s0, s0, 63
	s_mul_i32 s1, s92, 0x5000000
	v_or_b32_e32 v51, s0, v161
	s_mul_hi_i32 s0, s92, 0x5000000
	s_add_u32 s12, s76, s1
	s_addc_u32 s13, s77, s0
	s_not_b32 s0, s34
	s_lshl_b32 s0, s0, 7
	s_and_b32 s14, s0, 0x1f80
	v_ashrrev_i32_e32 v49, 6, v51
	v_lshl_add_u32 v80, v49, 4, s14
	v_mov_b64_e32 v[0:1], s[12:13]
	v_mad_i64_i32 v[0:1], s[0:1], v80, s88, v[0:1]
	s_lshl_b32 s0, s34, 1
	s_lshr_b32 s35, s14, 6
	s_and_b32 s0, s0, 0x180
	s_or_b32 s4, s35, 1
	s_lshl_b32 s18, s0, 1
	s_mul_i32 s0, s4, 0xa0000
	s_add_u32 s0, s12, s0
	s_addc_u32 s1, s13, 0
	v_and_b32_e32 v92, 15, v51
	s_add_u32 s0, s0, s18
	v_mul_u32_u24_e32 v2, 0x1400, v92
	s_addc_u32 s1, s1, 0
	v_lshlrev_b32_e32 v6, 3, v51
	v_and_b32_e32 v48, 63, v51
	v_lshl_add_u64 v[0:1], v[0:1], 0, s[18:19]
	v_lshlrev_b32_e32 v128, 1, v2
	s_add_u32 s6, s0, 0x1400
	v_and_b32_e32 v6, 0x78, v6
	v_lshl_add_u64 v[0:1], v[0:1], 0, v[128:129]
	s_addc_u32 s7, s1, 0
	v_add_u32_e32 v10, 0x200, v51
	v_lshlrev_b32_e32 v128, 1, v6
	v_mul_u32_u24_e32 v6, 0x1400, v48
	v_ashrrev_i32_e32 v8, 3, v51
	v_ashrrev_i32_e32 v64, 4, v51
	v_mov_b64_e32 v[2:3], s[6:7]
	v_lshlrev_b32_e32 v82, 1, v6
	v_mov_b32_e32 v83, v129
	v_and_b32_e32 v84, -8, v8
	v_ashrrev_i32_e32 v65, 4, v10
	v_mad_i64_i32 v[4:5], s[6:7], v64, s88, v[2:3]
	v_lshl_add_u64 v[32:33], s[0:1], 0, v[82:83]
	v_ashrrev_i32_e32 v85, 31, v84
	v_mad_i64_i32 v[2:3], s[6:7], v65, s88, v[2:3]
	v_lshl_add_u64 v[4:5], v[4:5], 0, v[128:129]
	v_lshl_add_u64 v[6:7], v[32:33], 0, s[90:91]
	v_lshlrev_b64 v[34:35], 1, v[84:85]
	v_lshl_add_u64 v[2:3], v[2:3], 0, v[128:129]
	v_lshl_add_u64 v[8:9], v[6:7], 0, v[34:35]
	global_load_dwordx4 v[16:19], v[4:5], off
	global_load_dwordx4 v[20:23], v[2:3], off
	global_load_dwordx4 v[24:27], v[8:9], off
	v_ashrrev_i32_e32 v2, 3, v10
	v_and_b32_e32 v86, -8, v2
	v_ashrrev_i32_e32 v87, 31, v86
	v_lshlrev_b64 v[36:37], 1, v[86:87]
	v_lshl_add_u64 v[2:3], v[6:7], 0, v[36:37]
	global_load_dwordx4 v[28:31], v[2:3], off
	v_and_b32_e32 v38, 48, v51
	v_mov_b32_e32 v39, v129
	v_lshl_add_u64 v[4:5], v[0:1], 0, v[38:39]
	v_add_co_u32_e32 v0, vcc, s61, v4
	s_mov_b64 s[6:7], 0x1000
	s_nop 0
	v_addc_co_u32_e32 v1, vcc, 0, v5, vcc
	global_load_dwordx4 v[0:3], v[0:1], off
	v_lshl_add_u64 v[12:13], v[4:5], 0, s[6:7]
	global_load_dwordx4 v[4:7], v[12:13], off offset:64
	global_load_dwordx4 v[8:11], v[12:13], off offset:128
	s_nop 0
	global_load_dwordx4 v[12:15], v[12:13], off offset:192
	v_mul_lo_u32 v93, v64, s89
	s_add_u32 s0, s0, 0xfff61400
	v_lshlrev_b32_e32 v95, 1, v48
	v_mul_lo_u32 v96, v65, s89
	v_mul_lo_u32 v97, v84, s30
	v_mul_lo_u32 v98, v86, s30
	v_add_u32_e32 v40, v93, v128
	s_addc_u32 s1, s1, -1
	v_or_b32_e32 v39, v97, v95
	v_add_u32_e32 v41, v96, v128
	s_barrier
	v_mul_u32_u24_e32 v94, 0x88, v92
	v_lshl_add_u32 v50, v94, 1, v38
	v_bfe_u32 v99, v51, 4, 2
	v_lshl_or_b32 v100, v99, 2, v80
	v_mov_b32_e32 v75, 0
	s_waitcnt vmcnt(7)
	ds_write_b128 v40, v[16:19]
	s_waitcnt vmcnt(6)
	ds_write_b128 v41, v[20:23]
	s_waitcnt vmcnt(5)
	ds_write_b16 v39, v24 offset:34816
	ds_write_b16_d16_hi v39, v24 offset:34960
	ds_write_b16 v39, v25 offset:35104
	ds_write_b16_d16_hi v39, v25 offset:35248
	ds_write_b16 v39, v26 offset:35392
	ds_write_b16_d16_hi v39, v26 offset:35536
	ds_write_b16 v39, v27 offset:35680
	ds_write_b16_d16_hi v39, v27 offset:35824
	v_or_b32_e32 v16, v98, v95
	v_mov_b64_e32 v[24:25], s[0:1]
	s_waitcnt vmcnt(4)
	ds_write_b16 v16, v28 offset:34816
	ds_write_b16_d16_hi v16, v28 offset:34960
	ds_write_b16 v16, v29 offset:35104
	ds_write_b16_d16_hi v16, v29 offset:35248
	ds_write_b16 v16, v30 offset:35392
	ds_write_b16_d16_hi v16, v30 offset:35536
	ds_write_b16 v16, v31 offset:35680
	ds_write_b16_d16_hi v16, v31 offset:35824
	v_mad_i64_i32 v[16:17], s[0:1], v64, s88, v[24:25]
	s_mov_b32 s0, 0xfff61800
	s_mov_b32 s1, -1
	v_lshl_add_u64 v[28:29], v[32:33], 0, s[0:1]
	v_mad_i64_i32 v[24:25], s[0:1], v65, s88, v[24:25]
	v_lshl_add_u64 v[16:17], v[16:17], 0, v[128:129]
	v_lshl_add_u64 v[20:21], v[28:29], 0, v[34:35]
	v_lshl_add_u64 v[24:25], v[24:25], 0, v[128:129]
	v_lshl_add_u64 v[28:29], v[28:29], 0, v[36:37]
	global_load_dwordx4 v[16:19], v[16:17], off
	s_nop 0
	global_load_dwordx4 v[20:23], v[20:21], off
	s_nop 0
	global_load_dwordx4 v[24:27], v[24:25], off
	s_nop 0
	global_load_dwordx4 v[28:31], v[28:29], off
	s_waitcnt lgkmcnt(0)
	s_barrier
; DEV f32x4 mfma16(bf16x8 a, bf16x8 b, f32x4 c) { return __builtin_amdgcn_mfma_f32_16x16x32_bf16(a, b, c, 0, 0, 0); }
; DEV void qk_tile(const bf16x8 (&qf)[MT][4], const u16* sK, f32x4 (&s)[MT][4], int fr, int fq) {
; #pragma unroll
;   for (int mt = 0; mt < MT; ++mt)
; #pragma unroll
;     for (int jt = 0; jt < 4; ++jt) s[mt][jt] = (f32x4){0.f, 0.f, 0.f, 0.f};
; #pragma unroll
;   for (int ks = 0; ks < 4; ++ks) {
;     bf16x8 b[4];
; #pragma unroll
;     for (int jt = 0; jt < 4; ++jt) b[jt] = *(const bf16x8*)(sK + (jt * 16 + fr) * KS + ks * 32 + fq * 8);
; #pragma unroll
;     for (int jt = 0; jt < 4; ++jt)
; #pragma unroll
;       for (int mt = 0; mt < MT; ++mt) s[mt][jt] = mfma16(qf[mt][ks], b[jt], s[mt][jt]);
;   }
; }
; DEV void sb_item(const Params& p, int item, unsigned char* smem) {
;     ...
;           const int sk = kt * 64 + jt * 16 + fr;
;           const float z = s[mt][jt][j] * scale;
;           const float sp = fmaxf(z, 0.f) + __logf(1.0f + __expf(-fabsf(z)));
;           lk[jt] = (sk < tq) ? -sp : 0.f;
;           lb[jt] = z - sp;
;           float x = lk[jt];
;           x += dpp_f<0x101>(x); x += dpp_f<0x102>(x); x += dpp_f<0x104>(x); x += dpp_f<0x108>(x);
;           inc[jt] = x;
;           tot[jt] = grp16_sum_fast(lk[jt]);
	ds_read_b128 v[32:35], v50
	ds_read_b128 v[52:55], v50 offset:64
	s_waitcnt vmcnt(7) lgkmcnt(1)
	v_mfma_f32_16x16x32_bf16 v[32:35], v[0:3], v[32:35], 0
	ds_read_b128 v[36:39], v50 offset:4352
	ds_read_b128 v[40:43], v50 offset:8704
	ds_read_b128 v[44:47], v50 offset:13056
	s_waitcnt vmcnt(6) lgkmcnt(3)
	v_mfma_f32_16x16x32_bf16 v[32:35], v[4:7], v[52:55], v[32:35]
	ds_read_b128 v[52:55], v50 offset:4416
	ds_read_b128 v[66:69], v50 offset:8896
	s_waitcnt lgkmcnt(4)
	v_mfma_f32_16x16x32_bf16 v[36:39], v[0:3], v[36:39], 0
	s_waitcnt lgkmcnt(1)
	v_mfma_f32_16x16x32_bf16 v[36:39], v[4:7], v[52:55], v[36:39]
	ds_read_b128 v[52:55], v50 offset:8768
	v_mfma_f32_16x16x32_bf16 v[40:43], v[0:3], v[40:43], 0
	s_waitcnt lgkmcnt(0)
	v_mfma_f32_16x16x32_bf16 v[40:43], v[4:7], v[52:55], v[40:43]
	ds_read_b128 v[52:55], v50 offset:13120
	v_mfma_f32_16x16x32_bf16 v[44:47], v[0:3], v[44:47], 0
	s_waitcnt lgkmcnt(0)
	v_mfma_f32_16x16x32_bf16 v[44:47], v[4:7], v[52:55], v[44:47]
	ds_read_b128 v[52:55], v50 offset:128
	s_waitcnt vmcnt(5) lgkmcnt(0)
	v_mfma_f32_16x16x32_bf16 v[32:35], v[8:11], v[52:55], v[32:35]
	ds_read_b128 v[52:55], v50 offset:4480
	s_waitcnt lgkmcnt(0)
	v_mfma_f32_16x16x32_bf16 v[36:39], v[8:11], v[52:55], v[36:39]
	ds_read_b128 v[52:55], v50 offset:8832
	s_waitcnt lgkmcnt(0)
	v_mfma_f32_16x16x32_bf16 v[56:59], v[8:11], v[52:55], v[40:43]
	s_nop 2
	ds_read_b128 v[40:43], v50 offset:13184
	s_waitcnt lgkmcnt(0)
	v_mfma_f32_16x16x32_bf16 v[60:63], v[8:11], v[40:43], v[44:47]
	ds_read_b128 v[40:43], v50 offset:192
	s_waitcnt vmcnt(4) lgkmcnt(0)
	v_mfma_f32_16x16x32_bf16 v[44:47], v[12:15], v[40:43], v[32:35]
	s_nop 2
	ds_read_b128 v[32:35], v50 offset:4544
	s_waitcnt lgkmcnt(0)
	v_mfma_f32_16x16x32_bf16 v[40:43], v[12:15], v[32:35], v[36:39]
	s_nop 1
	v_mul_f32_e32 v54, 0x3db504f3, v44
	v_mul_f32_e64 v32, |v54|, s31
	v_exp_f32_e32 v44, v32
	v_max_f32_e32 v52, 0, v54
	v_mfma_f32_16x16x32_bf16 v[36:39], v[12:15], v[66:69], v[56:59]
	ds_read_b128 v[32:35], v50 offset:13248
	v_add_f32_e32 v44, 1.0, v44
	s_nop 0
	v_mul_f32_e32 v59, 0x3db504f3, v40
	v_mul_f32_e64 v40, |v59|, s31
	s_nop 0
	s_nop 0
	v_log_f32_e32 v44, v44
	v_lshl_or_b32 v51, s4, 6, v92
	s_waitcnt lgkmcnt(0)
	v_mfma_f32_16x16x32_bf16 v[32:35], v[12:15], v[32:35], v[60:63]
	v_max_f32_e32 v55, 0, v59
	v_mul_f32_e32 v53, 0x3f317217, v44
	v_fma_f32 v53, v44, s29, -v53
	v_fmac_f32_e32 v53, 0x3377d1cf, v44
	v_fmac_f32_e32 v53, 0x3f317217, v44
	s_nop 0
	v_mul_f32_e32 v63, 0x3db504f3, v36
	v_mul_f32_e64 v36, |v63|, s31
	v_mov_b32_e32 v44, v53
	s_nop 0
	v_mov_b32_e32 v44, v44
	v_add_f32_e32 v56, v52, v44
	v_cmp_lt_i32_e32 vcc, v51, v100
	v_exp_f32_e32 v36, v36
	s_nop 0
	v_cndmask_b32_e64 v44, 0, -v56, vcc
	v_add_f32_e32 v36, 1.0, v36
	s_nop 0
	v_add_f32_dpp v52, v44, v44 row_shl:1 row_mask:0xf bank_mask:0xf bound_ctrl:1
	s_nop 1
	v_add_f32_dpp v52, v52, v52 row_shl:2 row_mask:0xf bank_mask:0xf bound_ctrl:1
	s_nop 1
	v_add_f32_dpp v57, v52, v52 row_shl:4 row_mask:0xf bank_mask:0xf bound_ctrl:1
	v_exp_f32_e32 v52, v40
	v_add_f32_dpp v40, v44, v44 row_ror:8 row_mask:0xf bank_mask:0xf bound_ctrl:1
	v_mov_b32_dpp v58, v57 row_shl:8 row_mask:0xf bank_mask:0xf bound_ctrl:1
	v_add_f32_e32 v44, 1.0, v52
	s_nop 0
	v_add_f32_dpp v40, v40, v40 row_ror:4 row_mask:0xf bank_mask:0xf bound_ctrl:1
	s_nop 0
	s_nop 0
	s_nop 0
	v_log_f32_e32 v53, v44
	v_or_b32_e32 v52, 16, v51
	v_add_f32_dpp v40, v40, v40 row_ror:2 row_mask:0xf bank_mask:0xf bound_ctrl:1
	v_mul_f32_e32 v60, 0x3f317217, v53
	v_fma_f32 v60, v53, s29, -v60
	v_fmac_f32_e32 v60, 0x3377d1cf, v53
	v_fmac_f32_e32 v60, 0x3f317217, v53
	s_nop 0
	v_mov_b32_dpp v44, v40 row_ror:1 row_mask:0xf bank_mask:0xf bound_ctrl:1
	s_nop 0
	v_mov_b32_e32 v53, v60
	s_nop 0
	v_mov_b32_e32 v53, v53
	v_add_f32_e32 v60, v55, v53
	v_cmp_lt_i32_e64 s[0:1], v52, v100
	v_cmp_gt_f32_e64 s[4:5], s84, v36
	s_nop 0
	v_cndmask_b32_e64 v53, 0, -v60, s[0:1]
	s_nop 1
	v_add_f32_dpp v55, v53, v53 row_shl:1 row_mask:0xf bank_mask:0xf bound_ctrl:1
	v_add_f32_dpp v53, v53, v53 row_ror:8 row_mask:0xf bank_mask:0xf bound_ctrl:1
	s_nop 0
	v_add_f32_dpp v55, v55, v55 row_shl:2 row_mask:0xf bank_mask:0xf bound_ctrl:1
	v_add_f32_dpp v53, v53, v53 row_ror:4 row_mask:0xf bank_mask:0xf bound_ctrl:1
	s_nop 0
	v_add_f32_dpp v61, v55, v55 row_shl:4 row_mask:0xf bank_mask:0xf bound_ctrl:1
	v_add_f32_dpp v66, v53, v53 row_ror:2 row_mask:0xf bank_mask:0xf bound_ctrl:1
	v_cndmask_b32_e64 v53, 0, 32, s[4:5]
	v_ldexp_f32 v36, v36, v53
	v_log_f32_e32 v53, v36
	v_or_b32_e32 v36, 32, v51
	v_max_f32_e32 v55, 0, v63
	v_mov_b32_dpp v62, v61 row_shl:8 row_mask:0xf bank_mask:0xf bound_ctrl:1
	v_mul_f32_e32 v68, 0x3f317217, v53
	v_fma_f32 v68, v53, s29, -v68
	v_fmac_f32_e32 v68, 0x3377d1cf, v53
	v_fmac_f32_e32 v68, 0x3f317217, v53
	v_cmp_lt_f32_e64 s[6:7], |v53|, s36
	v_mov_b32_dpp v67, v66 row_ror:1 row_mask:0xf bank_mask:0xf bound_ctrl:1
	s_nop 0
	v_cndmask_b32_e64 v53, v53, v68, s[6:7]
	v_cndmask_b32_e64 v68, 0, v171, s[4:5]
	v_sub_f32_e32 v53, v53, v68
	v_add_f32_e32 v68, v55, v53
	v_cmp_lt_i32_e64 s[4:5], v36, v100
	s_nop 1
	v_cndmask_b32_e64 v55, 0, -v68, s[4:5]
	s_nop 1
	v_add_f32_dpp v53, v55, v55 row_shl:1 row_mask:0xf bank_mask:0xf bound_ctrl:1
	v_add_f32_dpp v55, v55, v55 row_ror:8 row_mask:0xf bank_mask:0xf bound_ctrl:1
	s_nop 0
	v_add_f32_dpp v53, v53, v53 row_shl:2 row_mask:0xf bank_mask:0xf bound_ctrl:1
	v_add_f32_dpp v55, v55, v55 row_ror:4 row_mask:0xf bank_mask:0xf bound_ctrl:1
	s_nop 0
	v_add_f32_dpp v69, v53, v53 row_shl:4 row_mask:0xf bank_mask:0xf bound_ctrl:1
	v_mul_f32_e32 v53, 0x3db504f3, v32
	v_mul_f32_e64 v32, |v53|, s31
	v_exp_f32_e32 v32, v32
	v_add_f32_dpp v71, v55, v55 row_ror:2 row_mask:0xf bank_mask:0xf bound_ctrl:1
	v_max_f32_e32 v73, 0, v53
	v_mov_b32_dpp v70, v69 row_shl:8 row_mask:0xf bank_mask:0xf bound_ctrl:1
	v_add_f32_e32 v32, 1.0, v32
	s_nop 0
	v_mov_b32_dpp v72, v71 row_ror:1 row_mask:0xf bank_mask:0xf bound_ctrl:1
	s_nop 0
	s_nop 0
	s_nop 0
	v_log_f32_e32 v55, v32
	v_or_b32_e32 v32, 48, v51
	v_mul_f32_e32 v74, 0x3f317217, v55
	v_fma_f32 v74, v55, s29, -v74
	v_fmac_f32_e32 v74, 0x3377d1cf, v55
	v_fmac_f32_e32 v74, 0x3f317217, v55
	s_nop 0
	s_nop 1
	v_mov_b32_e32 v55, v74
	s_nop 0
	v_mov_b32_e32 v55, v55
	v_add_f32_e32 v76, v73, v55
	v_cmp_lt_i32_e64 s[6:7], v32, v100
	s_nop 1
	v_cndmask_b32_e64 v55, 0, -v76, s[6:7]
	s_nop 1
	v_add_f32_dpp v73, v55, v55 row_shl:1 row_mask:0xf bank_mask:0xf bound_ctrl:1
	v_add_f32_dpp v55, v55, v55 row_ror:8 row_mask:0xf bank_mask:0xf bound_ctrl:1
	s_nop 0
	v_add_f32_dpp v73, v73, v73 row_shl:2 row_mask:0xf bank_mask:0xf bound_ctrl:1
	v_add_f32_dpp v55, v55, v55 row_ror:4 row_mask:0xf bank_mask:0xf bound_ctrl:1
	s_nop 0
	v_add_f32_dpp v77, v73, v73 row_shl:4 row_mask:0xf bank_mask:0xf bound_ctrl:1
	v_add_f32_dpp v73, v55, v55 row_ror:2 row_mask:0xf bank_mask:0xf bound_ctrl:1
	v_mov_b32_e32 v55, 0
	v_mov_b32_dpp v78, v77 row_shl:8 row_mask:0xf bank_mask:0xf bound_ctrl:1
	v_mov_b32_dpp v74, v73 row_ror:1 row_mask:0xf bank_mask:0xf bound_ctrl:1
	s_and_saveexec_b64 s[10:11], s[6:7]
	s_cbranch_execz .LBB0_424
; DEV void sb_item(const Params& p, int item, unsigned char* smem) {
;     ...
;           const int sk = kt * 64 + jt * 16 + fr;
;           const float e = lb[jt] + (inc[jt] - lk[jt]) + after + run[mt][j];
;           const float a = (sk < tq) ? __expf(e) : 0.f;
;           sP[(mt * 16 + fq * 4 + j) * VS + jt * 16 + fr] = f2bf(a);
	v_add_f32_e32 v75, v77, v78
	v_sub_f32_e32 v53, v53, v76
	v_add_f32_e32 v75, v76, v75
	v_add_f32_e32 v53, v53, v75
	v_add_f32_e32 v53, 0, v53
	v_mul_f32_e32 v53, 0x3fb8aa3b, v53
	v_exp_f32_e32 v53, v53
	s_nop 0
	v_cvt_pk_bf16_f32 v75, v53, s0
